# v27 plus ple GEMM epilogue: X and G loads of each item prefetched 4 items ahead (ring of 4 slots) instead of load-wait-store per item
# speedup vs baseline: 1.0001x; 1.0001x over previous
; DI float bflo(unsigned w) { return __uint_as_float(w << 16); }
; DI float bfhi(unsigned w) { return __uint_as_float(w & 0xffff0000u); }
; template <class F> DI void epi_iter(const f32x4 (&acc)[2][2][4][2], const Unit& u, int wr, int wc, int fr, int fq, F f) {
;     const int row0 = u.pm * 256 + wr * 64 + fr, col0 = u.pn * 256 + wc * 32 + 8 * fq;
; #pragma unroll
;     for (int ai = 0; ai < 2; ++ai)
; #pragma unroll
;         for (int m = 0; m < 4; ++m)
; #pragma unroll
;             for (int bj = 0; bj < 2; ++bj) { f(row0 + ai * 128 + m * 16, col0 + bj * 128, acc[ai][bj][m][0], acc[ai][bj][m][1]); if ((m == 3) && bj) asm volatile("" ::: "memory"); }
;     DI void operator()(const f32x4 (&acc)[2][2][4][2], const Unit& u, int wr, int wc, int fr, int fq) const {
;         float* x = X; const bf16_t* g = G;
;         epi_iter(acc, u, wr, wc, fr, fq, [&](int row, int col, f32x4 v0, f32x4 v1) {
;             const size_t o = (size_t)row * DM + col;
;             f32x4 a = *(const f32x4*)(x + o), b = *(const f32x4*)(x + o + 4);
;             const u32x4 gw = *(const u32x4*)(g + o);
;             a[0] += v0[0] * bflo(gw.x); a[1] += v0[1] * bfhi(gw.x); a[2] += v0[2] * bflo(gw.y); a[3] += v0[3] * bfhi(gw.y);
;             b[0] += v1[0] * bflo(gw.z); b[1] += v1[1] * bfhi(gw.z); b[2] += v1[2] * bflo(gw.w); b[3] += v1[3] * bfhi(gw.w);
;             *(f32x4*)(x + o) = a; *(f32x4*)(x + o + 4) = b;
;         });
.LBB0_937:
	v_lshl_add_u32 v144, s65, 8, v146
	v_lshl_or_b32 v140, s64, 8, v153
	v_ashrrev_i32_e32 v145, 31, v144
	v_lshlrev_b64 v[142:143], 10, v[144:145]
	v_ashrrev_i32_e32 v141, 31, v140
	v_lshl_add_u64 v[164:165], v[142:143], 0, v[140:141]
	v_lshl_add_u64 v[168:169], v[164:165], 2, s[88:89]
	v_lshl_add_u64 v[164:165], v[164:165], 1, s[24:25]
	v_mov_b64_e32 v[184:185], v[168:169]
	v_mov_b64_e32 v[186:187], v[164:165]
	v_mov_b32_e32 v191, 0
	v_mov_b32_e32 v190, 0x0
	v_lshl_add_u64 v[188:189], v[184:185], 0, v[190:191]
	global_load_dwordx4 v[172:175], v[188:189], off
	global_load_dwordx4 v[176:179], v[188:189], off offset:16
	v_mov_b32_e32 v190, 0x0
	v_lshl_add_u64 v[188:189], v[186:187], 0, v[190:191]
	global_load_dwordx4 v[180:183], v[188:189], off
	v_mov_b32_e32 v190, 0x200
	v_lshl_add_u64 v[188:189], v[184:185], 0, v[190:191]
	global_load_dwordx4 v[212:215], v[188:189], off
	global_load_dwordx4 v[216:219], v[188:189], off offset:16
	v_mov_b32_e32 v190, 0x100
	v_lshl_add_u64 v[188:189], v[186:187], 0, v[190:191]
	global_load_dwordx4 v[220:223], v[188:189], off
	v_mov_b32_e32 v190, 0x10000
	v_lshl_add_u64 v[188:189], v[184:185], 0, v[190:191]
	global_load_dwordx4 v[224:227], v[188:189], off
	global_load_dwordx4 v[228:231], v[188:189], off offset:16
	v_mov_b32_e32 v190, 0x8000
	v_lshl_add_u64 v[188:189], v[186:187], 0, v[190:191]
	global_load_dwordx4 v[232:235], v[188:189], off
	v_mov_b32_e32 v190, 0x10200
	v_lshl_add_u64 v[188:189], v[184:185], 0, v[190:191]
	global_load_dwordx4 v[236:239], v[188:189], off
	global_load_dwordx4 v[240:243], v[188:189], off offset:16
	v_mov_b32_e32 v190, 0x8100
	v_lshl_add_u64 v[188:189], v[186:187], 0, v[190:191]
	global_load_dwordx4 v[244:247], v[188:189], off
	s_mov_b64 s[2:3], 0x20000
	s_and_b64 vcc, exec, s[38:39]
	s_waitcnt vmcnt(9)
	v_mov_b32_e32 v160, v172
	v_mov_b32_e32 v161, v173
	v_mov_b32_e32 v162, v174
	v_mov_b32_e32 v163, v175
	v_mov_b32_e32 v156, v176
	v_mov_b32_e32 v157, v177
	v_mov_b32_e32 v158, v178
	v_mov_b32_e32 v159, v179
	v_mov_b32_e32 v164, v180
	v_mov_b32_e32 v165, v181
	v_mov_b32_e32 v166, v182
	v_mov_b32_e32 v167, v183
	v_lshlrev_b32_e32 v170, 16, v164
	v_and_b32_e32 v171, 0xffff0000, v164
	v_pk_fma_f32 v[126:127], v[126:127], v[170:171], v[160:161]
	v_lshlrev_b32_e32 v160, 16, v165
	v_and_b32_e32 v161, 0xffff0000, v165
	v_pk_fma_f32 v[128:129], v[128:129], v[160:161], v[162:163]
	v_lshlrev_b32_e32 v160, 16, v166
	v_and_b32_e32 v161, 0xffff0000, v166
	v_pk_fma_f32 v[122:123], v[122:123], v[160:161], v[156:157]
	v_lshlrev_b32_e32 v156, 16, v167
	v_and_b32_e32 v157, 0xffff0000, v167
	v_pk_fma_f32 v[124:125], v[124:125], v[156:157], v[158:159]
	global_store_dwordx4 v[168:169], v[126:129], off
	global_store_dwordx4 v[168:169], v[122:125], off offset:16
	v_mov_b32_e32 v190, 0x20000
	v_lshl_add_u64 v[188:189], v[184:185], 0, v[190:191]
	global_load_dwordx4 v[172:175], v[188:189], off
	global_load_dwordx4 v[176:179], v[188:189], off offset:16
	v_mov_b32_e32 v190, 0x10000
	v_lshl_add_u64 v[188:189], v[186:187], 0, v[190:191]
	global_load_dwordx4 v[180:183], v[188:189], off
	s_nop 0
	v_or_b32_e32 v122, 0x80, v140
	v_ashrrev_i32_e32 v123, 31, v122
	v_lshl_add_u64 v[128:129], v[142:143], 0, v[122:123]
	v_lshl_add_u64 v[128:129], v[128:129], 1, s[24:25]
	s_waitcnt vmcnt(11)
	v_mov_b32_e32 v156, v212
	v_mov_b32_e32 v157, v213
	v_mov_b32_e32 v158, v214
	v_mov_b32_e32 v159, v215
	v_mov_b32_e32 v124, v216
	v_mov_b32_e32 v125, v217
	v_mov_b32_e32 v126, v218
	v_mov_b32_e32 v127, v219
	v_mov_b32_e32 v160, v220
	v_mov_b32_e32 v161, v221
	v_mov_b32_e32 v162, v222
	v_mov_b32_e32 v163, v223
	v_lshlrev_b32_e32 v128, 16, v160
	v_and_b32_e32 v129, 0xffff0000, v160
	v_pk_fma_f32 v[118:119], v[118:119], v[128:129], v[156:157]
	v_lshlrev_b32_e32 v128, 16, v161
	v_and_b32_e32 v129, 0xffff0000, v161
	v_pk_fma_f32 v[120:121], v[120:121], v[128:129], v[158:159]
	v_lshlrev_b32_e32 v128, 16, v162
	v_and_b32_e32 v129, 0xffff0000, v162
	v_pk_fma_f32 v[114:115], v[114:115], v[128:129], v[124:125]
	v_lshlrev_b32_e32 v124, 16, v163
	v_and_b32_e32 v125, 0xffff0000, v163
	v_pk_fma_f32 v[116:117], v[116:117], v[124:125], v[126:127]
	global_store_dwordx4 v[168:169], v[118:121], off offset:512
	global_store_dwordx4 v[168:169], v[114:117], off offset:528
	v_mov_b32_e32 v190, 0x20200
	v_lshl_add_u64 v[188:189], v[184:185], 0, v[190:191]
	global_load_dwordx4 v[212:215], v[188:189], off
	global_load_dwordx4 v[216:219], v[188:189], off offset:16
	v_mov_b32_e32 v190, 0x10100
	v_lshl_add_u64 v[188:189], v[186:187], 0, v[190:191]
	global_load_dwordx4 v[220:223], v[188:189], off
	s_nop 1
	v_or_b32_e32 v114, 16, v144
	v_ashrrev_i32_e32 v115, 31, v114
	v_lshlrev_b64 v[120:121], 10, v[114:115]
	v_lshl_add_u64 v[128:129], v[120:121], 0, v[140:141]
	v_lshl_add_u64 v[114:115], v[128:129], 2, s[88:89]
	v_lshl_add_u64 v[128:129], v[128:129], 1, s[24:25]
	s_waitcnt vmcnt(13)
	v_mov_b32_e32 v124, v224
	v_mov_b32_e32 v125, v225
	v_mov_b32_e32 v126, v226
	v_mov_b32_e32 v127, v227
	v_mov_b32_e32 v116, v228
	v_mov_b32_e32 v117, v229
	v_mov_b32_e32 v118, v230
	v_mov_b32_e32 v119, v231
	v_mov_b32_e32 v156, v232
	v_mov_b32_e32 v157, v233
	v_mov_b32_e32 v158, v234
	v_mov_b32_e32 v159, v235
	v_lshlrev_b32_e32 v128, 16, v156
	v_and_b32_e32 v129, 0xffff0000, v156
	v_pk_fma_f32 v[110:111], v[110:111], v[128:129], v[124:125]
	v_lshlrev_b32_e32 v124, 16, v157
	v_and_b32_e32 v125, 0xffff0000, v157
	v_pk_fma_f32 v[112:113], v[112:113], v[124:125], v[126:127]
	v_lshlrev_b32_e32 v124, 16, v158
	v_and_b32_e32 v125, 0xffff0000, v158
	v_pk_fma_f32 v[106:107], v[106:107], v[124:125], v[116:117]
	v_lshlrev_b32_e32 v116, 16, v159
	v_and_b32_e32 v117, 0xffff0000, v159
	v_pk_fma_f32 v[108:109], v[108:109], v[116:117], v[118:119]
	v_lshl_add_u64 v[116:117], v[120:121], 0, v[122:123]
	global_store_dwordx4 v[114:115], v[110:113], off
	global_store_dwordx4 v[114:115], v[106:109], off offset:16
	v_mov_b32_e32 v190, 0x30000
	v_lshl_add_u64 v[188:189], v[184:185], 0, v[190:191]
	global_load_dwordx4 v[224:227], v[188:189], off
	global_load_dwordx4 v[228:231], v[188:189], off offset:16
	v_mov_b32_e32 v190, 0x18000
	v_lshl_add_u64 v[188:189], v[186:187], 0, v[190:191]
	global_load_dwordx4 v[232:235], v[188:189], off
	v_lshl_add_u64 v[116:117], v[116:117], 1, s[24:25]
	s_nop 0
	s_waitcnt vmcnt(15)
; DI float bflo(unsigned w) { return __uint_as_float(w << 16); }
; DI float bfhi(unsigned w) { return __uint_as_float(w & 0xffff0000u); }
;     DI void operator()(const f32x4 (&acc)[2][2][4][2], const Unit& u, int wr, int wc, int fr, int fq) const {
;         float* x = X; const bf16_t* g = G;
;         epi_iter(acc, u, wr, wc, fr, fq, [&](int row, int col, f32x4 v0, f32x4 v1) {
;             const size_t o = (size_t)row * DM + col;
;             f32x4 a = *(const f32x4*)(x + o), b = *(const f32x4*)(x + o + 4);
;             const u32x4 gw = *(const u32x4*)(g + o);
;             a[0] += v0[0] * bflo(gw.x); a[1] += v0[1] * bfhi(gw.x); a[2] += v0[2] * bflo(gw.y); a[3] += v0[3] * bfhi(gw.y);
;             b[0] += v1[0] * bflo(gw.z); b[1] += v1[1] * bfhi(gw.z); b[2] += v1[2] * bflo(gw.w); b[3] += v1[3] * bfhi(gw.w);
;             *(f32x4*)(x + o) = a; *(f32x4*)(x + o + 4) = b;
;         });
	v_mov_b32_e32 v110, v236
	v_mov_b32_e32 v111, v237
	v_mov_b32_e32 v112, v238
	v_mov_b32_e32 v113, v239
	v_mov_b32_e32 v106, v240
	v_mov_b32_e32 v107, v241
	v_mov_b32_e32 v108, v242
	v_mov_b32_e32 v109, v243
	v_mov_b32_e32 v116, v244
	v_mov_b32_e32 v117, v245
	v_mov_b32_e32 v118, v246
	v_mov_b32_e32 v119, v247
	v_lshlrev_b32_e32 v120, 16, v116
	v_and_b32_e32 v121, 0xffff0000, v116
	v_pk_fma_f32 v[102:103], v[102:103], v[120:121], v[110:111]
	v_lshlrev_b32_e32 v110, 16, v117
	v_and_b32_e32 v111, 0xffff0000, v117
	v_pk_fma_f32 v[104:105], v[104:105], v[110:111], v[112:113]
	v_lshlrev_b32_e32 v110, 16, v118
	v_and_b32_e32 v111, 0xffff0000, v118
	v_pk_fma_f32 v[98:99], v[98:99], v[110:111], v[106:107]
	v_lshlrev_b32_e32 v106, 16, v119
	v_and_b32_e32 v107, 0xffff0000, v119
	v_pk_fma_f32 v[100:101], v[100:101], v[106:107], v[108:109]
	global_store_dwordx4 v[114:115], v[102:105], off offset:512
	global_store_dwordx4 v[114:115], v[98:101], off offset:528
	v_mov_b32_e32 v190, 0x30200
	v_lshl_add_u64 v[188:189], v[184:185], 0, v[190:191]
	global_load_dwordx4 v[236:239], v[188:189], off
	global_load_dwordx4 v[240:243], v[188:189], off offset:16
	v_mov_b32_e32 v190, 0x18100
	v_lshl_add_u64 v[188:189], v[186:187], 0, v[190:191]
	global_load_dwordx4 v[244:247], v[188:189], off
	s_nop 1
	v_or_b32_e32 v98, 32, v144
	v_ashrrev_i32_e32 v99, 31, v98
	v_lshlrev_b64 v[112:113], 10, v[98:99]
	v_lshl_add_u64 v[108:109], v[112:113], 0, v[140:141]
	v_lshl_add_u64 v[98:99], v[108:109], 2, s[88:89]
	v_lshl_add_u64 v[108:109], v[108:109], 1, s[24:25]
	s_nop 0
	s_waitcnt vmcnt(15)
	v_mov_b32_e32 v104, v172
	v_mov_b32_e32 v105, v173
	v_mov_b32_e32 v106, v174
	v_mov_b32_e32 v107, v175
	v_mov_b32_e32 v100, v176
	v_mov_b32_e32 v101, v177
	v_mov_b32_e32 v102, v178
	v_mov_b32_e32 v103, v179
	v_mov_b32_e32 v108, v180
	v_mov_b32_e32 v109, v181
	v_mov_b32_e32 v110, v182
	v_mov_b32_e32 v111, v183
	v_lshlrev_b32_e32 v114, 16, v108
	v_and_b32_e32 v115, 0xffff0000, v108
	v_pk_fma_f32 v[94:95], v[94:95], v[114:115], v[104:105]
	v_lshlrev_b32_e32 v104, 16, v109
	v_and_b32_e32 v105, 0xffff0000, v109
	v_pk_fma_f32 v[96:97], v[96:97], v[104:105], v[106:107]
	v_lshlrev_b32_e32 v104, 16, v110
	v_and_b32_e32 v105, 0xffff0000, v110
	v_pk_fma_f32 v[90:91], v[90:91], v[104:105], v[100:101]
	v_lshlrev_b32_e32 v100, 16, v111
	v_and_b32_e32 v101, 0xffff0000, v111
	v_pk_fma_f32 v[92:93], v[92:93], v[100:101], v[102:103]
	v_lshl_add_u64 v[100:101], v[112:113], 0, v[122:123]
	global_store_dwordx4 v[98:99], v[94:97], off
	global_store_dwordx4 v[98:99], v[90:93], off offset:16
	v_mov_b32_e32 v190, 0x80000
	v_lshl_add_u64 v[188:189], v[184:185], 0, v[190:191]
	global_load_dwordx4 v[172:175], v[188:189], off
	global_load_dwordx4 v[176:179], v[188:189], off offset:16
	v_mov_b32_e32 v190, 0x40000
	v_lshl_add_u64 v[188:189], v[186:187], 0, v[190:191]
	global_load_dwordx4 v[180:183], v[188:189], off
	v_lshl_add_u64 v[100:101], v[100:101], 1, s[24:25]
	s_nop 0
	s_waitcnt vmcnt(15)
	v_mov_b32_e32 v94, v212
	v_mov_b32_e32 v95, v213
	v_mov_b32_e32 v96, v214
	v_mov_b32_e32 v97, v215
	v_mov_b32_e32 v90, v216
	v_mov_b32_e32 v91, v217
	v_mov_b32_e32 v92, v218
	v_mov_b32_e32 v93, v219
	v_mov_b32_e32 v100, v220
	v_mov_b32_e32 v101, v221
	v_mov_b32_e32 v102, v222
	v_mov_b32_e32 v103, v223
	v_lshlrev_b32_e32 v104, 16, v100
	v_and_b32_e32 v105, 0xffff0000, v100
	v_pk_fma_f32 v[86:87], v[86:87], v[104:105], v[94:95]
	v_lshlrev_b32_e32 v94, 16, v101
	v_and_b32_e32 v95, 0xffff0000, v101
	v_pk_fma_f32 v[88:89], v[88:89], v[94:95], v[96:97]
	v_lshlrev_b32_e32 v94, 16, v102
	v_and_b32_e32 v95, 0xffff0000, v102
	v_pk_fma_f32 v[82:83], v[82:83], v[94:95], v[90:91]
	v_lshlrev_b32_e32 v90, 16, v103
	v_and_b32_e32 v91, 0xffff0000, v103
	v_pk_fma_f32 v[84:85], v[84:85], v[90:91], v[92:93]
	global_store_dwordx4 v[98:99], v[86:89], off offset:512
	global_store_dwordx4 v[98:99], v[82:85], off offset:528
	v_mov_b32_e32 v190, 0x80200
	v_lshl_add_u64 v[188:189], v[184:185], 0, v[190:191]
	global_load_dwordx4 v[212:215], v[188:189], off
	global_load_dwordx4 v[216:219], v[188:189], off offset:16
	v_mov_b32_e32 v190, 0x40100
	v_lshl_add_u64 v[188:189], v[186:187], 0, v[190:191]
	global_load_dwordx4 v[220:223], v[188:189], off
	s_nop 1
	v_or_b32_e32 v82, 48, v144
	v_ashrrev_i32_e32 v83, 31, v82
	v_lshlrev_b64 v[96:97], 10, v[82:83]
	v_lshl_add_u64 v[92:93], v[96:97], 0, v[140:141]
	v_lshl_add_u64 v[82:83], v[92:93], 2, s[88:89]
	v_lshl_add_u64 v[92:93], v[92:93], 1, s[24:25]
	s_nop 0
	s_waitcnt vmcnt(15)
	v_mov_b32_e32 v88, v224
	v_mov_b32_e32 v89, v225
	v_mov_b32_e32 v90, v226
	v_mov_b32_e32 v91, v227
	v_mov_b32_e32 v84, v228
	v_mov_b32_e32 v85, v229
	v_mov_b32_e32 v86, v230
	v_mov_b32_e32 v87, v231
	v_mov_b32_e32 v92, v232
	v_mov_b32_e32 v93, v233
	v_mov_b32_e32 v94, v234
	v_mov_b32_e32 v95, v235
	v_lshlrev_b32_e32 v98, 16, v92
	v_and_b32_e32 v99, 0xffff0000, v92
	v_pk_fma_f32 v[78:79], v[78:79], v[98:99], v[88:89]
	v_lshlrev_b32_e32 v88, 16, v93
	v_and_b32_e32 v89, 0xffff0000, v93
	v_pk_fma_f32 v[80:81], v[80:81], v[88:89], v[90:91]
	v_lshlrev_b32_e32 v88, 16, v94
	v_and_b32_e32 v89, 0xffff0000, v94
	v_pk_fma_f32 v[74:75], v[74:75], v[88:89], v[84:85]
	v_lshlrev_b32_e32 v84, 16, v95
	v_and_b32_e32 v85, 0xffff0000, v95
	v_pk_fma_f32 v[76:77], v[76:77], v[84:85], v[86:87]
	v_lshl_add_u64 v[84:85], v[96:97], 0, v[122:123]
	global_store_dwordx4 v[82:83], v[78:81], off
	global_store_dwordx4 v[82:83], v[74:77], off offset:16
	v_mov_b32_e32 v190, 0x90000
	v_lshl_add_u64 v[188:189], v[184:185], 0, v[190:191]
	global_load_dwordx4 v[224:227], v[188:189], off
	global_load_dwordx4 v[228:231], v[188:189], off offset:16
	v_mov_b32_e32 v190, 0x48000
	v_lshl_add_u64 v[188:189], v[186:187], 0, v[190:191]
	global_load_dwordx4 v[232:235], v[188:189], off
	v_lshl_add_u64 v[84:85], v[84:85], 1, s[24:25]
	s_nop 0
	s_waitcnt vmcnt(15)
; DI float bflo(unsigned w) { return __uint_as_float(w << 16); }
; DI float bfhi(unsigned w) { return __uint_as_float(w & 0xffff0000u); }
; template <class F> DI void epi_iter(const f32x4 (&acc)[2][2][4][2], const Unit& u, int wr, int wc, int fr, int fq, F f) {
;     ...
;     for (int ai = 0; ai < 2; ++ai)
; #pragma unroll
;         for (int m = 0; m < 4; ++m)
; #pragma unroll
;             for (int bj = 0; bj < 2; ++bj) { f(row0 + ai * 128 + m * 16, col0 + bj * 128, acc[ai][bj][m][0], acc[ai][bj][m][1]); if ((m == 3) && bj) asm volatile("" ::: "memory"); }
;     DI void operator()(const f32x4 (&acc)[2][2][4][2], const Unit& u, int wr, int wc, int fr, int fq) const {
;         float* x = X; const bf16_t* g = G;
;         epi_iter(acc, u, wr, wc, fr, fq, [&](int row, int col, f32x4 v0, f32x4 v1) {
;             const size_t o = (size_t)row * DM + col;
;             f32x4 a = *(const f32x4*)(x + o), b = *(const f32x4*)(x + o + 4);
;             const u32x4 gw = *(const u32x4*)(g + o);
;             a[0] += v0[0] * bflo(gw.x); a[1] += v0[1] * bfhi(gw.x); a[2] += v0[2] * bflo(gw.y); a[3] += v0[3] * bfhi(gw.y);
;             b[0] += v1[0] * bflo(gw.z); b[1] += v1[1] * bfhi(gw.z); b[2] += v1[2] * bflo(gw.w); b[3] += v1[3] * bfhi(gw.w);
;             *(f32x4*)(x + o) = a; *(f32x4*)(x + o + 4) = b;
;         });
	v_mov_b32_e32 v78, v236
	v_mov_b32_e32 v79, v237
	v_mov_b32_e32 v80, v238
	v_mov_b32_e32 v81, v239
	v_mov_b32_e32 v74, v240
	v_mov_b32_e32 v75, v241
	v_mov_b32_e32 v76, v242
	v_mov_b32_e32 v77, v243
	v_mov_b32_e32 v84, v244
	v_mov_b32_e32 v85, v245
	v_mov_b32_e32 v86, v246
	v_mov_b32_e32 v87, v247
	v_lshlrev_b32_e32 v88, 16, v84
	v_and_b32_e32 v89, 0xffff0000, v84
	v_pk_fma_f32 v[70:71], v[70:71], v[88:89], v[78:79]
	v_lshlrev_b32_e32 v78, 16, v85
	v_and_b32_e32 v79, 0xffff0000, v85
	v_pk_fma_f32 v[72:73], v[72:73], v[78:79], v[80:81]
	v_lshlrev_b32_e32 v78, 16, v86
	v_and_b32_e32 v79, 0xffff0000, v86
	v_pk_fma_f32 v[66:67], v[66:67], v[78:79], v[74:75]
	v_lshlrev_b32_e32 v74, 16, v87
	v_and_b32_e32 v75, 0xffff0000, v87
	v_lshl_add_u64 v[80:81], v[142:143], 0, s[2:3]
	v_pk_fma_f32 v[68:69], v[68:69], v[74:75], v[76:77]
	global_store_dwordx4 v[82:83], v[70:73], off offset:512
	global_store_dwordx4 v[82:83], v[66:69], off offset:528
	v_mov_b32_e32 v190, 0x90200
	v_lshl_add_u64 v[188:189], v[184:185], 0, v[190:191]
	global_load_dwordx4 v[236:239], v[188:189], off
	global_load_dwordx4 v[240:243], v[188:189], off offset:16
	v_mov_b32_e32 v190, 0x48100
	v_lshl_add_u64 v[188:189], v[186:187], 0, v[190:191]
	global_load_dwordx4 v[244:247], v[188:189], off
	v_lshl_add_u64 v[76:77], v[80:81], 0, v[140:141]
	s_mov_b64 s[2:3], 0x24000
	v_lshl_add_u64 v[66:67], v[76:77], 2, s[88:89]
	v_lshl_add_u64 v[76:77], v[76:77], 1, s[24:25]
	s_nop 0
	s_waitcnt vmcnt(15)
	v_mov_b32_e32 v72, v172
	v_mov_b32_e32 v73, v173
	v_mov_b32_e32 v74, v174
	v_mov_b32_e32 v75, v175
	v_mov_b32_e32 v68, v176
	v_mov_b32_e32 v69, v177
	v_mov_b32_e32 v70, v178
	v_mov_b32_e32 v71, v179
	v_mov_b32_e32 v76, v180
	v_mov_b32_e32 v77, v181
	v_mov_b32_e32 v78, v182
	v_mov_b32_e32 v79, v183
	v_lshlrev_b32_e32 v82, 16, v76
	v_and_b32_e32 v83, 0xffff0000, v76
	v_pk_fma_f32 v[62:63], v[62:63], v[82:83], v[72:73]
	v_lshlrev_b32_e32 v72, 16, v77
	v_and_b32_e32 v73, 0xffff0000, v77
	v_pk_fma_f32 v[64:65], v[64:65], v[72:73], v[74:75]
	v_lshlrev_b32_e32 v72, 16, v78
	v_and_b32_e32 v73, 0xffff0000, v78
	v_pk_fma_f32 v[58:59], v[58:59], v[72:73], v[68:69]
	v_lshlrev_b32_e32 v68, 16, v79
	v_and_b32_e32 v69, 0xffff0000, v79
	v_pk_fma_f32 v[60:61], v[60:61], v[68:69], v[70:71]
	v_lshl_add_u64 v[68:69], v[80:81], 0, v[122:123]
	global_store_dwordx4 v[66:67], v[62:65], off
	global_store_dwordx4 v[66:67], v[58:61], off offset:16
	v_mov_b32_e32 v190, 0xa0000
	v_lshl_add_u64 v[188:189], v[184:185], 0, v[190:191]
	global_load_dwordx4 v[172:175], v[188:189], off
	global_load_dwordx4 v[176:179], v[188:189], off offset:16
	v_mov_b32_e32 v190, 0x50000
	v_lshl_add_u64 v[188:189], v[186:187], 0, v[190:191]
	global_load_dwordx4 v[180:183], v[188:189], off
	v_lshl_add_u64 v[68:69], v[68:69], 1, s[24:25]
	s_nop 0
	s_waitcnt vmcnt(15)
	v_mov_b32_e32 v62, v212
	v_mov_b32_e32 v63, v213
	v_mov_b32_e32 v64, v214
	v_mov_b32_e32 v65, v215
	v_mov_b32_e32 v58, v216
	v_mov_b32_e32 v59, v217
	v_mov_b32_e32 v60, v218
	v_mov_b32_e32 v61, v219
	v_mov_b32_e32 v68, v220
	v_mov_b32_e32 v69, v221
	v_mov_b32_e32 v70, v222
	v_mov_b32_e32 v71, v223
	v_lshlrev_b32_e32 v72, 16, v68
	v_and_b32_e32 v73, 0xffff0000, v68
	v_pk_fma_f32 v[54:55], v[54:55], v[72:73], v[62:63]
	v_lshlrev_b32_e32 v62, 16, v69
	v_and_b32_e32 v63, 0xffff0000, v69
	v_pk_fma_f32 v[56:57], v[56:57], v[62:63], v[64:65]
	v_lshlrev_b32_e32 v62, 16, v70
	v_and_b32_e32 v63, 0xffff0000, v70
	v_pk_fma_f32 v[50:51], v[50:51], v[62:63], v[58:59]
	v_lshlrev_b32_e32 v58, 16, v71
	v_and_b32_e32 v59, 0xffff0000, v71
	v_lshl_add_u64 v[64:65], v[142:143], 0, s[2:3]
	v_pk_fma_f32 v[52:53], v[52:53], v[58:59], v[60:61]
	v_lshl_add_u64 v[60:61], v[64:65], 0, v[140:141]
	global_store_dwordx4 v[66:67], v[54:57], off offset:512
	global_store_dwordx4 v[66:67], v[50:53], off offset:528
	v_mov_b32_e32 v190, 0xa0200
	v_lshl_add_u64 v[188:189], v[184:185], 0, v[190:191]
	global_load_dwordx4 v[212:215], v[188:189], off
	global_load_dwordx4 v[216:219], v[188:189], off offset:16
	v_mov_b32_e32 v190, 0x50100
	v_lshl_add_u64 v[188:189], v[186:187], 0, v[190:191]
	global_load_dwordx4 v[220:223], v[188:189], off
	s_mov_b64 s[2:3], 0x28000
	s_nop 0
	v_lshl_add_u64 v[50:51], v[60:61], 2, s[88:89]
	v_lshl_add_u64 v[60:61], v[60:61], 1, s[24:25]
	s_nop 0
	s_waitcnt vmcnt(15)
	v_mov_b32_e32 v56, v224
	v_mov_b32_e32 v57, v225
	v_mov_b32_e32 v58, v226
	v_mov_b32_e32 v59, v227
	v_mov_b32_e32 v52, v228
	v_mov_b32_e32 v53, v229
	v_mov_b32_e32 v54, v230
	v_mov_b32_e32 v55, v231
	v_mov_b32_e32 v60, v232
	v_mov_b32_e32 v61, v233
	v_mov_b32_e32 v62, v234
	v_mov_b32_e32 v63, v235
	v_lshlrev_b32_e32 v66, 16, v60
	v_and_b32_e32 v67, 0xffff0000, v60
	v_pk_fma_f32 v[46:47], v[46:47], v[66:67], v[56:57]
	v_lshlrev_b32_e32 v56, 16, v61
	v_and_b32_e32 v57, 0xffff0000, v61
	v_pk_fma_f32 v[48:49], v[48:49], v[56:57], v[58:59]
	v_lshlrev_b32_e32 v56, 16, v62
	v_and_b32_e32 v57, 0xffff0000, v62
	v_pk_fma_f32 v[42:43], v[42:43], v[56:57], v[52:53]
	v_lshlrev_b32_e32 v52, 16, v63
	v_and_b32_e32 v53, 0xffff0000, v63
	v_pk_fma_f32 v[44:45], v[44:45], v[52:53], v[54:55]
	v_lshl_add_u64 v[52:53], v[64:65], 0, v[122:123]
	global_store_dwordx4 v[50:51], v[46:49], off
	global_store_dwordx4 v[50:51], v[42:45], off offset:16
	v_mov_b32_e32 v190, 0xb0000
	v_lshl_add_u64 v[188:189], v[184:185], 0, v[190:191]
	global_load_dwordx4 v[224:227], v[188:189], off
	global_load_dwordx4 v[228:231], v[188:189], off offset:16
	v_mov_b32_e32 v190, 0x58000
	v_lshl_add_u64 v[188:189], v[186:187], 0, v[190:191]
	global_load_dwordx4 v[232:235], v[188:189], off
	v_lshl_add_u64 v[52:53], v[52:53], 1, s[24:25]
	s_nop 0
	s_waitcnt vmcnt(15)
; DI float bflo(unsigned w) { return __uint_as_float(w << 16); }
; DI float bfhi(unsigned w) { return __uint_as_float(w & 0xffff0000u); }
; template <class F> DI void epi_iter(const f32x4 (&acc)[2][2][4][2], const Unit& u, int wr, int wc, int fr, int fq, F f) {
;     ...
;     for (int ai = 0; ai < 2; ++ai)
; #pragma unroll
;         for (int m = 0; m < 4; ++m)
; #pragma unroll
;             for (int bj = 0; bj < 2; ++bj) { f(row0 + ai * 128 + m * 16, col0 + bj * 128, acc[ai][bj][m][0], acc[ai][bj][m][1]); if ((m == 3) && bj) asm volatile("" ::: "memory"); }
;     DI void operator()(const f32x4 (&acc)[2][2][4][2], const Unit& u, int wr, int wc, int fr, int fq) const {
;         float* x = X; const bf16_t* g = G;
;         epi_iter(acc, u, wr, wc, fr, fq, [&](int row, int col, f32x4 v0, f32x4 v1) {
;             const size_t o = (size_t)row * DM + col;
;             f32x4 a = *(const f32x4*)(x + o), b = *(const f32x4*)(x + o + 4);
;             const u32x4 gw = *(const u32x4*)(g + o);
;             a[0] += v0[0] * bflo(gw.x); a[1] += v0[1] * bfhi(gw.x); a[2] += v0[2] * bflo(gw.y); a[3] += v0[3] * bfhi(gw.y);
;             b[0] += v1[0] * bflo(gw.z); b[1] += v1[1] * bfhi(gw.z); b[2] += v1[2] * bflo(gw.w); b[3] += v1[3] * bfhi(gw.w);
;             *(f32x4*)(x + o) = a; *(f32x4*)(x + o + 4) = b;
;         });
	v_mov_b32_e32 v46, v236
	v_mov_b32_e32 v47, v237
	v_mov_b32_e32 v48, v238
	v_mov_b32_e32 v49, v239
	v_mov_b32_e32 v42, v240
	v_mov_b32_e32 v43, v241
	v_mov_b32_e32 v44, v242
	v_mov_b32_e32 v45, v243
	v_mov_b32_e32 v52, v244
	v_mov_b32_e32 v53, v245
	v_mov_b32_e32 v54, v246
	v_mov_b32_e32 v55, v247
	v_lshlrev_b32_e32 v56, 16, v52
	v_and_b32_e32 v57, 0xffff0000, v52
	v_pk_fma_f32 v[38:39], v[38:39], v[56:57], v[46:47]
	v_lshlrev_b32_e32 v46, 16, v53
	v_and_b32_e32 v47, 0xffff0000, v53
	v_pk_fma_f32 v[40:41], v[40:41], v[46:47], v[48:49]
	v_lshlrev_b32_e32 v46, 16, v54
	v_and_b32_e32 v47, 0xffff0000, v54
	v_pk_fma_f32 v[34:35], v[34:35], v[46:47], v[42:43]
	v_lshlrev_b32_e32 v42, 16, v55
	v_and_b32_e32 v43, 0xffff0000, v55
	v_lshl_add_u64 v[48:49], v[142:143], 0, s[2:3]
	v_pk_fma_f32 v[36:37], v[36:37], v[42:43], v[44:45]
	v_lshl_add_u64 v[44:45], v[48:49], 0, v[140:141]
	global_store_dwordx4 v[50:51], v[38:41], off offset:512
	global_store_dwordx4 v[50:51], v[34:37], off offset:528
	v_mov_b32_e32 v190, 0xb0200
	v_lshl_add_u64 v[188:189], v[184:185], 0, v[190:191]
	global_load_dwordx4 v[236:239], v[188:189], off
	global_load_dwordx4 v[240:243], v[188:189], off offset:16
	v_mov_b32_e32 v190, 0x58100
	v_lshl_add_u64 v[188:189], v[186:187], 0, v[190:191]
	global_load_dwordx4 v[244:247], v[188:189], off
	s_mov_b64 s[2:3], 0x2c000
	s_nop 0
	v_lshl_add_u64 v[34:35], v[44:45], 2, s[88:89]
	v_lshl_add_u64 v[44:45], v[44:45], 1, s[24:25]
	s_nop 0
	s_waitcnt vmcnt(15)
	v_mov_b32_e32 v40, v172
	v_mov_b32_e32 v41, v173
	v_mov_b32_e32 v42, v174
	v_mov_b32_e32 v43, v175
	v_mov_b32_e32 v36, v176
	v_mov_b32_e32 v37, v177
	v_mov_b32_e32 v38, v178
	v_mov_b32_e32 v39, v179
	v_mov_b32_e32 v44, v180
	v_mov_b32_e32 v45, v181
	v_mov_b32_e32 v46, v182
	v_mov_b32_e32 v47, v183
	v_lshlrev_b32_e32 v50, 16, v44
	v_and_b32_e32 v51, 0xffff0000, v44
	v_pk_fma_f32 v[30:31], v[30:31], v[50:51], v[40:41]
	v_lshlrev_b32_e32 v40, 16, v45
	v_and_b32_e32 v41, 0xffff0000, v45
	v_pk_fma_f32 v[32:33], v[32:33], v[40:41], v[42:43]
	v_lshlrev_b32_e32 v40, 16, v46
	v_and_b32_e32 v41, 0xffff0000, v46
	v_pk_fma_f32 v[26:27], v[26:27], v[40:41], v[36:37]
	v_lshlrev_b32_e32 v36, 16, v47
	v_and_b32_e32 v37, 0xffff0000, v47
	v_pk_fma_f32 v[28:29], v[28:29], v[36:37], v[38:39]
	v_lshl_add_u64 v[36:37], v[48:49], 0, v[122:123]
	global_store_dwordx4 v[34:35], v[30:33], off
	global_store_dwordx4 v[34:35], v[26:29], off offset:16
	v_lshl_add_u64 v[36:37], v[36:37], 1, s[24:25]
	s_nop 0
	s_waitcnt vmcnt(12)
	v_mov_b32_e32 v30, v212
	v_mov_b32_e32 v31, v213
	v_mov_b32_e32 v32, v214
	v_mov_b32_e32 v33, v215
	v_mov_b32_e32 v26, v216
	v_mov_b32_e32 v27, v217
	v_mov_b32_e32 v28, v218
	v_mov_b32_e32 v29, v219
	v_mov_b32_e32 v36, v220
	v_mov_b32_e32 v37, v221
	v_mov_b32_e32 v38, v222
	v_mov_b32_e32 v39, v223
	v_lshlrev_b32_e32 v40, 16, v36
	v_and_b32_e32 v41, 0xffff0000, v36
	v_pk_fma_f32 v[22:23], v[22:23], v[40:41], v[30:31]
	v_lshlrev_b32_e32 v30, 16, v37
	v_and_b32_e32 v31, 0xffff0000, v37
	v_pk_fma_f32 v[24:25], v[24:25], v[30:31], v[32:33]
	v_lshlrev_b32_e32 v30, 16, v38
	v_and_b32_e32 v31, 0xffff0000, v38
	v_pk_fma_f32 v[18:19], v[18:19], v[30:31], v[26:27]
	v_lshlrev_b32_e32 v26, 16, v39
	v_and_b32_e32 v27, 0xffff0000, v39
	v_lshl_add_u64 v[32:33], v[142:143], 0, s[2:3]
	v_pk_fma_f32 v[20:21], v[20:21], v[26:27], v[28:29]
	v_lshl_add_u64 v[28:29], v[32:33], 0, v[140:141]
	global_store_dwordx4 v[34:35], v[22:25], off offset:512
	global_store_dwordx4 v[34:35], v[18:21], off offset:528
	s_mov_b64 s[2:3], -1
	s_nop 0
	v_lshl_add_u64 v[18:19], v[28:29], 2, s[88:89]
	v_lshl_add_u64 v[28:29], v[28:29], 1, s[24:25]
	s_nop 0
	s_waitcnt vmcnt(9)
	v_mov_b32_e32 v24, v224
	v_mov_b32_e32 v25, v225
	v_mov_b32_e32 v26, v226
	v_mov_b32_e32 v27, v227
	v_mov_b32_e32 v20, v228
	v_mov_b32_e32 v21, v229
	v_mov_b32_e32 v22, v230
	v_mov_b32_e32 v23, v231
	v_mov_b32_e32 v28, v232
	v_mov_b32_e32 v29, v233
	v_mov_b32_e32 v30, v234
	v_mov_b32_e32 v31, v235
	v_lshlrev_b32_e32 v34, 16, v28
	v_and_b32_e32 v35, 0xffff0000, v28
	v_pk_fma_f32 v[14:15], v[14:15], v[34:35], v[24:25]
	v_lshlrev_b32_e32 v24, 16, v29
	v_and_b32_e32 v25, 0xffff0000, v29
	v_pk_fma_f32 v[16:17], v[16:17], v[24:25], v[26:27]
	v_lshlrev_b32_e32 v24, 16, v30
	v_and_b32_e32 v25, 0xffff0000, v30
	v_pk_fma_f32 v[10:11], v[10:11], v[24:25], v[20:21]
	v_lshlrev_b32_e32 v20, 16, v31
	v_and_b32_e32 v21, 0xffff0000, v31
	v_pk_fma_f32 v[12:13], v[12:13], v[20:21], v[22:23]
	v_lshl_add_u64 v[20:21], v[32:33], 0, v[122:123]
	global_store_dwordx4 v[18:19], v[14:17], off
	global_store_dwordx4 v[18:19], v[10:13], off offset:16
	v_lshl_add_u64 v[20:21], v[20:21], 1, s[24:25]
	s_nop 0
	s_waitcnt vmcnt(6)
	v_mov_b32_e32 v14, v236
	v_mov_b32_e32 v15, v237
	v_mov_b32_e32 v16, v238
	v_mov_b32_e32 v17, v239
	v_mov_b32_e32 v10, v240
	v_mov_b32_e32 v11, v241
	v_mov_b32_e32 v12, v242
	v_mov_b32_e32 v13, v243
	v_mov_b32_e32 v20, v244
	v_mov_b32_e32 v21, v245
	v_mov_b32_e32 v22, v246
	v_mov_b32_e32 v23, v247
	v_lshlrev_b32_e32 v24, 16, v20
	v_and_b32_e32 v25, 0xffff0000, v20
	v_pk_fma_f32 v[6:7], v[6:7], v[24:25], v[14:15]
	v_lshlrev_b32_e32 v14, 16, v21
	v_and_b32_e32 v15, 0xffff0000, v21
	v_pk_fma_f32 v[8:9], v[8:9], v[14:15], v[16:17]
	v_lshlrev_b32_e32 v14, 16, v22
	v_and_b32_e32 v15, 0xffff0000, v22
	v_pk_fma_f32 v[2:3], v[2:3], v[14:15], v[10:11]
	v_lshlrev_b32_e32 v10, 16, v23
	v_and_b32_e32 v11, 0xffff0000, v23
	v_pk_fma_f32 v[4:5], v[4:5], v[10:11], v[12:13]
	global_store_dwordx4 v[18:19], v[6:9], off offset:512
	global_store_dwordx4 v[18:19], v[2:5], off offset:528
	s_cbranch_vccnz .LBB0_924
	s_andn2_b64 vcc, exec, s[46:47]
	s_cbranch_vccnz .LBB0_923
	s_barrier
	s_branch .LBB0_923
